# P4's half of the w_gate|w_up conversion moved to P2's tail workgroups (they have slack), on top of lean MB=3 K-loops P5+P9
# baseline (speedup 1.0000x reference)
.LBB0_526:
	s_add_i32 s6, s96, 0xffffff40
	s_cmpk_eq_i32 s42, 0x100
	s_cselect_b64 s[4:5], -1, 0
	s_and_b64 s[2:3], s[4:5], exec
	s_cselect_b32 s10, s6, s96
	s_cmp_lt_i32 s10, 0
	s_cbranch_scc1 .LBB0_535
	s_movk_i32 s6, 0x580
	s_and_b64 s[2:3], s[4:5], exec
	s_cselect_b32 s2, s6, 0x580
	s_cmp_ge_u32 s10, s2
	s_cbranch_scc1 .LBB0_535
	s_load_dwordx4 s[16:19], s[0:1], 0xa8
	s_and_b64 s[4:5], s[4:5], exec
	s_cselect_b32 s3, 64, s42
	s_add_u32 s4, s36, 0x1bd3c000
	v_mov_b32_e32 v54, v184
	s_addc_u32 s5, s37, 0
	s_lshl_b32 s6, s10, 2
	v_and_b32_e32 v0, 0x7f, v54
	v_and_b32_e32 v5, 63, v54
	s_and_b32 s6, s6, 0x3ffc0
	s_waitcnt lgkmcnt(0)
	v_mov_b32_e32 v1, s19
	v_mov_b32_e32 v3, s17
	v_cmp_gt_u32_e32 vcc, 64, v0
	s_lshl_b32 s8, s10, 7
	v_ashrrev_i32_e32 v4, 7, v54
	v_or_b32_e32 v2, s6, v5
	v_cndmask_b32_e32 v1, v1, v3, vcc
	v_mov_b32_e32 v0, s18
	v_mov_b32_e32 v3, s16
	s_and_b32 s6, s8, 0x780
	v_cndmask_b32_e32 v0, v0, v3, vcc
	v_add_u32_e32 v3, s6, v4
	s_movk_i32 s9, 0x5800
	v_mad_i64_i32 v[6:7], s[6:7], v3, s9, v[0:1]
	v_lshlrev_b32_e32 v2, 2, v2
	v_mov_b32_e32 v3, 0
	v_lshl_add_u64 v[22:23], v[6:7], 0, v[2:3]
	s_mov_b32 s6, 0x16000
	v_add_co_u32_e32 v14, vcc, s6, v22
	s_mov_b32 s6, 0x2c000
	s_waitcnt vmcnt(0)
	v_addc_co_u32_e32 v15, vcc, 0, v23, vcc
	v_add_co_u32_e32 v16, vcc, s6, v22
	s_mov_b32 s6, 0x42000
	s_nop 0
	v_addc_co_u32_e32 v17, vcc, 0, v23, vcc
	v_add_co_u32_e32 v18, vcc, s6, v22
	s_mov_b32 s6, 0x58000
	s_nop 0
	v_addc_co_u32_e32 v19, vcc, 0, v23, vcc
	v_add_co_u32_e32 v20, vcc, s6, v22
	s_mov_b32 s6, 0x6e000
	s_nop 0
	v_addc_co_u32_e32 v21, vcc, 0, v23, vcc
	v_add_co_u32_e32 v24, vcc, s6, v22
	s_mov_b32 s6, 0x84000
	s_nop 0
	v_addc_co_u32_e32 v25, vcc, 0, v23, vcc
	v_add_co_u32_e32 v26, vcc, s6, v22
	s_mov_b32 s6, 0x9a000
	s_nop 0
	v_addc_co_u32_e32 v27, vcc, 0, v23, vcc
	v_add_co_u32_e32 v28, vcc, s6, v22
	s_mov_b32 s6, 0xb0000
	s_nop 0
	v_addc_co_u32_e32 v29, vcc, 0, v23, vcc
	global_load_dword v6, v[22:23], off nt
	global_load_dword v7, v[14:15], off nt
	global_load_dword v8, v[16:17], off nt
	global_load_dword v9, v[18:19], off nt
	global_load_dword v10, v[20:21], off nt
	global_load_dword v11, v[24:25], off nt
	global_load_dword v12, v[26:27], off nt
	global_load_dword v13, v[28:29], off nt
	v_add_co_u32_e32 v24, vcc, s6, v22
	s_mov_b32 s6, 0xc6000
	s_nop 0
	v_addc_co_u32_e32 v25, vcc, 0, v23, vcc
	v_add_co_u32_e32 v26, vcc, s6, v22
	s_mov_b32 s6, 0xdc000
	s_nop 0
	v_addc_co_u32_e32 v27, vcc, 0, v23, vcc
	v_add_co_u32_e32 v28, vcc, s6, v22
	s_mov_b32 s6, 0xf2000
	s_nop 0
	v_addc_co_u32_e32 v29, vcc, 0, v23, vcc
	v_add_co_u32_e32 v30, vcc, s6, v22
	s_mov_b32 s6, 0x108000
	s_nop 0
	v_addc_co_u32_e32 v31, vcc, 0, v23, vcc
	v_add_co_u32_e32 v32, vcc, s6, v22
	s_mov_b32 s6, 0x11e000
	s_nop 0
	v_addc_co_u32_e32 v33, vcc, 0, v23, vcc
	v_add_co_u32_e32 v34, vcc, s6, v22
	s_mov_b32 s6, 0x134000
	s_nop 0
	v_addc_co_u32_e32 v35, vcc, 0, v23, vcc
	v_add_co_u32_e32 v36, vcc, s6, v22
	s_mov_b32 s6, 0x14a000
	s_nop 0
	v_addc_co_u32_e32 v37, vcc, 0, v23, vcc
	v_add_co_u32_e32 v38, vcc, s6, v22
	s_mov_b32 s6, 0x160000
	s_nop 0
	v_addc_co_u32_e32 v39, vcc, 0, v23, vcc
	global_load_dword v14, v[24:25], off nt
	global_load_dword v15, v[26:27], off nt
	global_load_dword v16, v[28:29], off nt
	global_load_dword v17, v[30:31], off nt
	global_load_dword v18, v[32:33], off nt
	global_load_dword v19, v[34:35], off nt
	global_load_dword v20, v[36:37], off nt
	global_load_dword v21, v[38:39], off nt
	v_add_co_u32_e32 v24, vcc, s6, v22
	s_mov_b32 s6, 0x176000
	s_nop 0
	v_addc_co_u32_e32 v25, vcc, 0, v23, vcc
	v_add_co_u32_e32 v26, vcc, s6, v22
	s_mov_b32 s6, 0x18c000
	s_nop 0
	v_addc_co_u32_e32 v27, vcc, 0, v23, vcc
	v_add_co_u32_e32 v28, vcc, s6, v22
	s_mov_b32 s6, 0x1a2000
	s_nop 0
	v_addc_co_u32_e32 v29, vcc, 0, v23, vcc
	v_add_co_u32_e32 v30, vcc, s6, v22
	s_mov_b32 s6, 0x1b8000
	s_nop 0
	v_addc_co_u32_e32 v31, vcc, 0, v23, vcc
	v_add_co_u32_e32 v40, vcc, s6, v22
	s_mov_b32 s6, 0x1ce000
	s_nop 0
	v_addc_co_u32_e32 v41, vcc, 0, v23, vcc
	v_add_co_u32_e32 v42, vcc, s6, v22
	s_mov_b32 s6, 0x1e4000
	s_nop 0
	v_addc_co_u32_e32 v43, vcc, 0, v23, vcc
	v_add_co_u32_e32 v44, vcc, s6, v22
	s_mov_b32 s6, 0x1fa000
	s_nop 0
	v_addc_co_u32_e32 v45, vcc, 0, v23, vcc
	v_add_co_u32_e32 v46, vcc, s6, v22
	s_mov_b32 s6, 0x210000
	s_nop 0
	v_addc_co_u32_e32 v47, vcc, 0, v23, vcc
	global_load_dword v32, v[24:25], off nt
	global_load_dword v33, v[26:27], off nt
	global_load_dword v34, v[28:29], off nt
	global_load_dword v35, v[30:31], off nt
	global_load_dword v36, v[40:41], off nt
	global_load_dword v37, v[42:43], off nt
	global_load_dword v38, v[44:45], off nt
	global_load_dword v39, v[46:47], off nt
	v_add_co_u32_e32 v24, vcc, s6, v22
	s_mov_b32 s6, 0x226000
	s_nop 0
	v_addc_co_u32_e32 v25, vcc, 0, v23, vcc
	v_add_co_u32_e32 v26, vcc, s6, v22
	s_mov_b32 s6, 0x23c000
	s_nop 0
	v_addc_co_u32_e32 v27, vcc, 0, v23, vcc
	v_add_co_u32_e32 v28, vcc, s6, v22
	s_mov_b32 s6, 0x252000
	s_nop 0
	v_addc_co_u32_e32 v29, vcc, 0, v23, vcc
	v_add_co_u32_e32 v30, vcc, s6, v22
	s_mov_b32 s6, 0x268000
	s_nop 0
	v_addc_co_u32_e32 v31, vcc, 0, v23, vcc
	v_add_co_u32_e32 v48, vcc, s6, v22
	s_mov_b32 s6, 0x27e000
	s_nop 0
	v_addc_co_u32_e32 v49, vcc, 0, v23, vcc
	v_add_co_u32_e32 v50, vcc, s6, v22
	s_mov_b32 s6, 0x294000
	s_nop 0
	v_addc_co_u32_e32 v51, vcc, 0, v23, vcc
	v_add_co_u32_e32 v52, vcc, s6, v22
	s_mov_b32 s6, 0x2aa000
	s_nop 0
	v_addc_co_u32_e32 v53, vcc, 0, v23, vcc
	v_add_co_u32_e32 v22, vcc, s6, v22
	v_lshlrev_b32_e32 v2, 1, v54
	s_nop 0
	v_addc_co_u32_e32 v23, vcc, 0, v23, vcc
	global_load_dword v40, v[24:25], off nt
	global_load_dword v41, v[26:27], off nt
	global_load_dword v42, v[28:29], off nt
	global_load_dword v43, v[30:31], off nt
	global_load_dword v44, v[48:49], off nt
	global_load_dword v45, v[50:51], off nt
	global_load_dword v46, v[52:53], off nt
	global_load_dword v47, v[22:23], off nt
	v_lshrrev_b32_e32 v22, 4, v54
	v_and_b32_e32 v2, 0x78, v2
	v_and_b32_e32 v22, 4, v22
	v_and_b32_e32 v23, 3, v54
	v_or3_b32 v30, v22, v23, v2
	v_lshlrev_b32_e32 v2, 3, v54
	v_add_u32_e32 v24, 0x200, v54
	v_add_u32_e32 v26, 0x400, v54
	v_add_u32_e32 v28, 0x600, v54
	v_and_b32_e32 v2, 0x78, v2
	v_ashrrev_i32_e32 v22, 4, v54
	s_movk_i32 s6, 0x110
	v_ashrrev_i32_e32 v24, 4, v24
	v_ashrrev_i32_e32 v26, 4, v26
	v_ashrrev_i32_e32 v28, 4, v28
	s_lshl_b32 s12, s3, 7
	s_mov_b32 s11, 0
	v_mul_lo_u32 v23, v22, s6
	v_mul_lo_u32 v25, v24, s6
	v_mul_lo_u32 v27, v26, s6
	v_mul_lo_u32 v29, v28, s6
	v_mul_u32_u24_e32 v30, 0x110, v30
	v_add_u32_e32 v31, s12, v4
	s_movk_i32 s13, 0x7fff
	v_lshlrev_b32_e32 v2, 1, v2
	s_barrier
	s_branch .LBB0_530

.LBB0_700:
	s_andn2_b64 vcc, exec, s[4:5]
	s_cbranch_vccnz .LBB0_696
	v_readlane_b32 s4, v255, 14
	v_readlane_b32 s5, v255, 15
	s_andn2_b64 vcc, exec, s[4:5]
	s_branch .LBB0_729
	s_load_dwordx4 s[4:7], s[0:1], 0xa8
	v_mov_b32_e32 v24, v184
	v_readlane_b32 s2, v255, 7
	v_and_b32_e32 v0, 0x7f, v24
	s_waitcnt vmcnt(0)
	v_and_b32_e32 v5, 63, v24
	s_waitcnt lgkmcnt(0)
	v_mov_b32_e32 v1, s7
	v_mov_b32_e32 v3, s5
	v_cmp_gt_u32_e32 vcc, 64, v0
	v_ashrrev_i32_e32 v4, 7, v24
	v_or_b32_e32 v2, s2, v5
	v_cndmask_b32_e32 v1, v1, v3, vcc
	v_mov_b32_e32 v0, s6
	v_mov_b32_e32 v3, s4
	v_readlane_b32 s2, v255, 8
	v_cndmask_b32_e32 v0, v0, v3, vcc
	s_lshl_b32 s8, s45, 7
	v_add_u32_e32 v3, s2, v4
	v_mad_i64_i32 v[6:7], s[4:5], v3, s16, v[0:1]
	v_ashrrev_i32_e32 v3, 31, v2
	v_lshl_add_u64 v[2:3], v[2:3], 2, v[6:7]
	v_add_co_u32_e32 v8, vcc, s95, v2
	s_mov_b32 s2, 0x2c000
	s_nop 0
	v_addc_co_u32_e32 v9, vcc, 0, v3, vcc
	v_add_co_u32_e32 v10, vcc, s2, v2
	s_mov_b32 s2, 0x42000
	s_nop 0
	v_addc_co_u32_e32 v11, vcc, 0, v3, vcc
	v_add_co_u32_e32 v12, vcc, s2, v2
	s_mov_b32 s2, 0x58000
	s_nop 0
	v_addc_co_u32_e32 v13, vcc, 0, v3, vcc
	v_add_co_u32_e32 v14, vcc, s2, v2
	s_mov_b32 s2, 0x6e000
	s_nop 0
	v_addc_co_u32_e32 v15, vcc, 0, v3, vcc
	v_add_co_u32_e32 v16, vcc, s2, v2
	s_mov_b32 s2, 0x84000
	s_nop 0
	v_addc_co_u32_e32 v17, vcc, 0, v3, vcc
	v_add_co_u32_e32 v18, vcc, s2, v2
	s_mov_b32 s2, 0x9a000
	s_nop 0
	v_addc_co_u32_e32 v19, vcc, 0, v3, vcc
	v_add_co_u32_e32 v20, vcc, s2, v2
	s_mov_b32 s2, 0xb0000
	s_nop 0
	v_addc_co_u32_e32 v21, vcc, 0, v3, vcc
	global_load_dword v6, v[2:3], off nt
	global_load_dword v7, v[8:9], off nt
	s_nop 0
	global_load_dword v8, v[10:11], off nt
	global_load_dword v9, v[12:13], off nt
	s_nop 0
	global_load_dword v10, v[14:15], off nt
	global_load_dword v11, v[16:17], off nt
	global_load_dword v12, v[18:19], off nt
	global_load_dword v13, v[20:21], off nt
	v_add_co_u32_e32 v14, vcc, s2, v2
	s_mov_b32 s2, 0xc6000
	s_nop 0
	v_addc_co_u32_e32 v15, vcc, 0, v3, vcc
	v_add_co_u32_e32 v16, vcc, s2, v2
	s_mov_b32 s2, 0xdc000
	s_nop 0
	v_addc_co_u32_e32 v17, vcc, 0, v3, vcc
	v_add_co_u32_e32 v18, vcc, s2, v2
	s_mov_b32 s2, 0xf2000
	s_nop 0
	v_addc_co_u32_e32 v19, vcc, 0, v3, vcc
	v_add_co_u32_e32 v20, vcc, s2, v2
	s_mov_b32 s2, 0x108000
	s_nop 0
	v_addc_co_u32_e32 v21, vcc, 0, v3, vcc
	v_add_co_u32_e32 v22, vcc, s2, v2
	s_mov_b32 s2, 0x11e000
	s_nop 0
	v_addc_co_u32_e32 v23, vcc, 0, v3, vcc
	v_add_co_u32_e32 v26, vcc, s2, v2
	s_mov_b32 s2, 0x134000
	s_nop 0
	v_addc_co_u32_e32 v27, vcc, 0, v3, vcc
	v_add_co_u32_e32 v30, vcc, s2, v2
	s_mov_b32 s2, 0x14a000
	s_nop 0
	v_addc_co_u32_e32 v31, vcc, 0, v3, vcc
	v_add_co_u32_e32 v32, vcc, s2, v2
	s_mov_b32 s2, 0x160000
	s_nop 0
	v_addc_co_u32_e32 v33, vcc, 0, v3, vcc
	global_load_dword v14, v[14:15], off nt
	s_nop 0
	global_load_dword v15, v[16:17], off nt
	s_nop 0
	global_load_dword v16, v[18:19], off nt
	global_load_dword v25, v[20:21], off nt
	global_load_dword v28, v[22:23], off nt
	global_load_dword v29, v[26:27], off nt
	s_nop 0
	global_load_dword v30, v[30:31], off nt
	s_nop 0
	global_load_dword v31, v[32:33], off nt
	v_add_co_u32_e32 v18, vcc, s2, v2
	s_mov_b32 s2, 0x176000
	s_nop 0
	v_addc_co_u32_e32 v19, vcc, 0, v3, vcc
	v_add_co_u32_e32 v20, vcc, s2, v2
	s_mov_b32 s2, 0x18c000
	s_nop 0
	v_addc_co_u32_e32 v21, vcc, 0, v3, vcc
	v_add_co_u32_e32 v22, vcc, s2, v2
	s_mov_b32 s2, 0x1a2000
	s_nop 0
	v_addc_co_u32_e32 v23, vcc, 0, v3, vcc
	v_add_co_u32_e32 v26, vcc, s2, v2
	s_mov_b32 s2, 0x1b8000
	s_nop 0
	v_addc_co_u32_e32 v27, vcc, 0, v3, vcc
	v_add_co_u32_e32 v36, vcc, s2, v2
	s_mov_b32 s2, 0x1ce000
	s_nop 0
	v_addc_co_u32_e32 v37, vcc, 0, v3, vcc
	v_add_co_u32_e32 v38, vcc, s2, v2
	s_mov_b32 s2, 0x1e4000
	s_nop 0
	v_addc_co_u32_e32 v39, vcc, 0, v3, vcc
	v_add_co_u32_e32 v40, vcc, s2, v2
	s_mov_b32 s2, 0x1fa000
	s_nop 0
	v_addc_co_u32_e32 v41, vcc, 0, v3, vcc
	v_add_co_u32_e32 v42, vcc, s2, v2
	s_mov_b32 s2, 0x210000
	s_nop 0
	v_addc_co_u32_e32 v43, vcc, 0, v3, vcc
	global_load_dword v32, v[18:19], off nt
	global_load_dword v33, v[20:21], off nt
	global_load_dword v34, v[22:23], off nt
	global_load_dword v35, v[26:27], off nt
	s_nop 0
	global_load_dword v36, v[36:37], off nt
	s_nop 0
	global_load_dword v37, v[38:39], off nt
	s_nop 0
	global_load_dword v38, v[40:41], off nt
	global_load_dword v39, v[42:43], off nt
	v_add_co_u32_e32 v18, vcc, s2, v2
	s_mov_b32 s2, 0x226000
	s_nop 0
	v_addc_co_u32_e32 v19, vcc, 0, v3, vcc
	v_add_co_u32_e32 v20, vcc, s2, v2
	s_mov_b32 s2, 0x23c000
	s_nop 0
	v_addc_co_u32_e32 v21, vcc, 0, v3, vcc
	v_add_co_u32_e32 v22, vcc, s2, v2
	s_mov_b32 s2, 0x252000
	s_nop 0
	v_addc_co_u32_e32 v23, vcc, 0, v3, vcc
	v_add_co_u32_e32 v26, vcc, s2, v2
	s_mov_b32 s2, 0x268000
	s_nop 0
	v_addc_co_u32_e32 v27, vcc, 0, v3, vcc
	v_add_co_u32_e32 v44, vcc, s2, v2
	s_mov_b32 s2, 0x27e000
	s_nop 0
	v_addc_co_u32_e32 v45, vcc, 0, v3, vcc
	v_add_co_u32_e32 v46, vcc, s2, v2
	s_mov_b32 s2, 0x294000
	s_nop 0
	v_addc_co_u32_e32 v47, vcc, 0, v3, vcc
	v_add_co_u32_e32 v48, vcc, s2, v2
	s_mov_b32 s2, 0x2aa000
	s_nop 0
	v_addc_co_u32_e32 v49, vcc, 0, v3, vcc
	v_add_co_u32_e32 v2, vcc, s2, v2
	v_lshrrev_b32_e32 v17, 4, v24
	s_nop 0
	v_addc_co_u32_e32 v3, vcc, 0, v3, vcc
	global_load_dword v40, v[18:19], off nt
	global_load_dword v41, v[20:21], off nt
	global_load_dword v42, v[22:23], off nt
	global_load_dword v43, v[26:27], off nt
	s_nop 0
	global_load_dword v44, v[44:45], off nt
	s_nop 0
	global_load_dword v45, v[46:47], off nt
	s_nop 0
	global_load_dword v46, v[48:49], off nt
	s_nop 0
	global_load_dword v2, v[2:3], off nt
	v_lshlrev_b32_e32 v3, 1, v24
	v_and_b32_e32 v3, 0x78, v3
	v_and_b32_e32 v17, 4, v17
	v_and_b32_e32 v18, 3, v24
	v_or3_b32 v3, v17, v18, v3
	v_lshlrev_b32_e32 v17, 3, v24
	v_add_u32_e32 v19, 0x200, v24
	v_add_u32_e32 v21, 0x400, v24
	v_add_u32_e32 v23, 0x600, v24
	v_and_b32_e32 v48, 0x78, v17
	v_ashrrev_i32_e32 v17, 4, v24
	v_ashrrev_i32_e32 v19, 4, v19
	v_ashrrev_i32_e32 v21, 4, v21
	v_ashrrev_i32_e32 v23, 4, v23
	s_mov_b32 s2, 0
	v_mul_lo_u32 v18, v17, s97
	v_mul_lo_u32 v20, v19, s97
	v_mul_lo_u32 v22, v21, s97
	v_mul_lo_u32 v24, v23, s97
	v_mul_u32_u24_e32 v26, 0x110, v3
	v_add_u32_e32 v27, 0x8000, v4
	v_lshlrev_b32_e32 v176, 1, v48
	s_mov_b32 s10, s45
	s_barrier
	s_branch .LBB0_724
